# grid barrier: all waiters poll the cross-XCD arrival counter (target = (generation+1) x populated XCDs); the release-generation hop and the two release atomics are gone
# speedup vs baseline: 1.0024x; 1.0021x over previous
; __device__ __forceinline__ unsigned xb_ld(unsigned* p)              { return __hip_atomic_load(p, __ATOMIC_RELAXED, __HIP_MEMORY_SCOPE_AGENT); }
; __device__ __forceinline__ unsigned xb_add(unsigned* p, unsigned v) { return __hip_atomic_fetch_add(p, v, __ATOMIC_RELAXED, __HIP_MEMORY_SCOPE_AGENT); }
; #define XB_SPIN(cond, bar) do { unsigned _sp = 0; while (cond) { __builtin_amdgcn_s_sleep(1); \
;     if ((++_sp & 255u) == 0u) { if (xb_ld(&(bar)[XB_TMO])) break; if (_sp > XB_SPIN_CAP) { atomicAdd(&(bar)[XB_TMO], 1u); break; } } } } while (0)
; __device__ __forceinline__ void xcd_barrier(const XcdBarrier& b) {
;     ...
;         const unsigned old = xb_add(&bar[XB_XSUB(b.x)], 1u);
;         const unsigned gen = old / nloc;
;         if (old + 1u == (gen + 1u) * nloc) {
;             __builtin_amdgcn_fence(__ATOMIC_RELEASE, "agent");
;             asm volatile("s_waitcnt vmcnt(0)" ::: "memory");
;             const unsigned og = xb_add(&bar[XB_TOP], 1u);
;             const unsigned tg = og / nx;
;             if (og + 1u == (tg + 1u) * nx) xb_add(&bar[XB_TOPGEN], 1u);
;             else XB_SPIN(xb_ld(&bar[XB_TOPGEN]) == tg, bar);
;             __builtin_amdgcn_fence(__ATOMIC_ACQUIRE, "agent");
;             xb_add(&bar[XB_XGEN(b.x)], 1u);
;             asm volatile("s_waitcnt vmcnt(0)" ::: "memory");
;         } else {
;             XB_SPIN(xb_ld(&bar[XB_XGEN(b.x)]) == gen, bar);
;             __builtin_amdgcn_fence(__ATOMIC_ACQUIRE, "agent");
;             asm volatile("s_waitcnt vmcnt(0)" ::: "memory");
;         }
.LBB0_202:
	v_readlane_b32 s4, v254, 6
	s_lshl_b32 s4, s4, 8
	v_readlane_b32 s6, v254, 4
	v_readlane_b32 s7, v254, 5
	s_add_u32 s4, s6, s4
	s_addc_u32 s5, s7, 0
	v_mov_b32_e32 v1, 0x1000
	v_mov_b32_e32 v3, 1
	global_atomic_add v3, v1, v3, s[4:5] offset:1024 sc0
	v_cvt_f32_u32_e32 v1, v2
	v_sub_u32_e32 v4, 0, v2
	v_rcp_iflag_f32_e32 v1, v1
	s_nop 0
	v_mul_f32_e32 v1, 0x4f7ffffe, v1
	v_cvt_u32_f32_e32 v1, v1
	v_mul_lo_u32 v4, v4, v1
	v_mul_hi_u32 v4, v1, v4
	v_add_u32_e32 v1, v1, v4
	s_waitcnt vmcnt(0)
	v_mul_hi_u32 v1, v3, v1
	v_mul_lo_u32 v4, v1, v2
	v_sub_u32_e32 v4, v3, v4
	v_add_u32_e32 v5, 1, v1
	v_cmp_ge_u32_e32 vcc, v4, v2
	v_add_u32_e32 v3, 1, v3
	s_nop 0
	v_cndmask_b32_e32 v1, v1, v5, vcc
	v_sub_u32_e32 v5, v4, v2
	v_cndmask_b32_e32 v4, v4, v5, vcc
	v_add_u32_e32 v5, 1, v1
	v_cmp_ge_u32_e32 vcc, v4, v2
	s_nop 1
	v_cndmask_b32_e32 v1, v1, v5, vcc
	v_mul_lo_u32 v4, v2, v1
	v_add_u32_e32 v2, v4, v2
	v_cmp_ne_u32_e32 vcc, v3, v2
	s_and_saveexec_b64 s[6:7], vcc
	s_xor_b64 s[6:7], exec, s[6:7]
	s_cbranch_execz .LBB0_216
	s_waitcnt lgkmcnt(0)
	s_add_u32 s16, s94, 0x83500
	s_addc_u32 s17, s95, 0
	v_mad_u32_u24 v4, v1, v0, v0
	v_mov_b32_e32 v0, 0
	global_load_dword v0, v0, s[16:17] offset:-256 sc1
	s_waitcnt vmcnt(0)
	v_cmp_gt_u32_e32 vcc, v4, v0
	s_and_saveexec_b64 s[8:9], vcc
	s_cbranch_execz .LBB0_215
	s_add_u32 s10, s94, 0x80200
	s_addc_u32 s11, s95, 0
	s_mov_b32 s12, 1
	s_mov_b64 s[18:19], 0
	v_mov_b32_e32 v0, 0
	s_branch .LBB0_206

; __device__ __forceinline__ unsigned xb_ld(unsigned* p)              { return __hip_atomic_load(p, __ATOMIC_RELAXED, __HIP_MEMORY_SCOPE_AGENT); }
; __device__ __forceinline__ unsigned xb_add(unsigned* p, unsigned v) { return __hip_atomic_fetch_add(p, v, __ATOMIC_RELAXED, __HIP_MEMORY_SCOPE_AGENT); }
; #define XB_SPIN(cond, bar) do { unsigned _sp = 0; while (cond) { __builtin_amdgcn_s_sleep(1); \
;     if ((++_sp & 255u) == 0u) { if (xb_ld(&(bar)[XB_TMO])) break; if (_sp > XB_SPIN_CAP) { atomicAdd(&(bar)[XB_TMO], 1u); break; } } } } while (0)
; __device__ __forceinline__ void xcd_barrier(const XcdBarrier& b) {
;     ...
;             else XB_SPIN(xb_ld(&bar[XB_TOPGEN]) == tg, bar);
;             __builtin_amdgcn_fence(__ATOMIC_ACQUIRE, "agent");
;             xb_add(&bar[XB_XGEN(b.x)], 1u);
;             asm volatile("s_waitcnt vmcnt(0)" ::: "memory");
;         } else {
;             XB_SPIN(xb_ld(&bar[XB_XGEN(b.x)]) == gen, bar);
.LBB0_208:
	global_load_dword v2, v0, s[16:17] offset:-256 sc1
	s_add_i32 s12, s12, 1
	s_mov_b64 s[24:25], -1
	s_waitcnt vmcnt(0)
	v_cmp_le_u32_e32 vcc, v4, v2
	s_orn2_b64 s[22:23], vcc, exec
	s_branch .LBB0_205

; __device__ __forceinline__ unsigned xb_ld(unsigned* p)              { return __hip_atomic_load(p, __ATOMIC_RELAXED, __HIP_MEMORY_SCOPE_AGENT); }
; __device__ __forceinline__ unsigned xb_add(unsigned* p, unsigned v) { return __hip_atomic_fetch_add(p, v, __ATOMIC_RELAXED, __HIP_MEMORY_SCOPE_AGENT); }
; #define XB_SPIN(cond, bar) do { unsigned _sp = 0; while (cond) { __builtin_amdgcn_s_sleep(1); \
;     if ((++_sp & 255u) == 0u) { if (xb_ld(&(bar)[XB_TMO])) break; if (_sp > XB_SPIN_CAP) { atomicAdd(&(bar)[XB_TMO], 1u); break; } } } } while (0)
; __device__ __forceinline__ void xcd_barrier(const XcdBarrier& b) {
;     ...
;             asm volatile("s_waitcnt vmcnt(0)" ::: "memory");
;             const unsigned og = xb_add(&bar[XB_TOP], 1u);
;             const unsigned tg = og / nx;
;             if (og + 1u == (tg + 1u) * nx) xb_add(&bar[XB_TOPGEN], 1u);
;             else XB_SPIN(xb_ld(&bar[XB_TOPGEN]) == tg, bar);
;             __builtin_amdgcn_fence(__ATOMIC_ACQUIRE, "agent");
.LBB0_219:
	s_or_b64 exec, exec, s[8:9]
	v_cvt_f32_u32_e32 v3, v0
	s_waitcnt vmcnt(0)
	v_readfirstlane_b32 s6, v2
	s_add_u32 s8, s94, 0x83500
	s_addc_u32 s9, s95, 0
	v_rcp_iflag_f32_e32 v3, v3
	v_add_u32_e32 v1, s6, v1
	v_add_u32_e32 v4, 1, v1
	s_mov_b64 s[10:11], -1
	v_mul_f32_e32 v2, 0x4f7ffffe, v3
	v_cvt_u32_f32_e32 v2, v2
	v_sub_u32_e32 v3, 0, v0
	v_mul_lo_u32 v3, v3, v2
	v_mul_hi_u32 v3, v2, v3
	v_add_u32_e32 v2, v2, v3
	v_mul_hi_u32 v2, v1, v2
	v_mul_lo_u32 v3, v2, v0
	v_sub_u32_e32 v1, v1, v3
	v_add_u32_e32 v5, 1, v2
	v_cmp_ge_u32_e32 vcc, v1, v0
	v_sub_u32_e32 v3, v1, v0
	s_nop 0
	v_cndmask_b32_e32 v2, v2, v5, vcc
	v_cndmask_b32_e32 v1, v1, v3, vcc
	v_add_u32_e32 v3, 1, v2
	v_cmp_ge_u32_e32 vcc, v1, v0
	s_nop 1
	v_cndmask_b32_e32 v2, v2, v3, vcc
	v_mul_lo_u32 v1, v0, v2
	v_add_u32_e32 v0, v1, v0
	v_mov_b32_e32 v5, v0
	v_cmp_ne_u32_e32 vcc, v4, v0
	v_mov_b64_e32 v[0:1], s[8:9]
	s_and_saveexec_b64 s[6:7], vcc
	s_cbranch_execz .LBB0_231
	v_mov_b32_e32 v0, 0
	global_load_dword v1, v0, s[8:9] offset:-256 sc1
	s_mov_b64 s[18:19], 0
	s_waitcnt vmcnt(0)
	v_cmp_gt_u32_e32 vcc, v5, v1
	s_and_saveexec_b64 s[16:17], vcc
	s_cbranch_execz .LBB0_230
	s_add_u32 s10, s94, 0x80200
	s_addc_u32 s11, s95, 0
	s_mov_b32 s12, 1
	s_branch .LBB0_223

; __device__ __forceinline__ unsigned xb_ld(unsigned* p)              { return __hip_atomic_load(p, __ATOMIC_RELAXED, __HIP_MEMORY_SCOPE_AGENT); }
; #define XB_SPIN(cond, bar) do { unsigned _sp = 0; while (cond) { __builtin_amdgcn_s_sleep(1); \
;     if ((++_sp & 255u) == 0u) { if (xb_ld(&(bar)[XB_TMO])) break; if (_sp > XB_SPIN_CAP) { atomicAdd(&(bar)[XB_TMO], 1u); break; } } } } while (0)
; __device__ __forceinline__ void xcd_barrier(const XcdBarrier& b) {
;     ...
;             else XB_SPIN(xb_ld(&bar[XB_TOPGEN]) == tg, bar);
.LBB0_225:
	global_load_dword v1, v0, s[8:9] offset:-256 sc1
	s_add_i32 s12, s12, 1
	s_mov_b64 s[22:23], -1
	s_waitcnt vmcnt(0)
	v_cmp_le_u32_e32 vcc, v5, v1
	s_orn2_b64 s[26:27], vcc, exec
	s_branch .LBB0_222

; __device__ __forceinline__ unsigned xb_add(unsigned* p, unsigned v) { return __hip_atomic_fetch_add(p, v, __ATOMIC_RELAXED, __HIP_MEMORY_SCOPE_AGENT); }
; __device__ __forceinline__ void xcd_barrier(const XcdBarrier& b) {
;     ...
;             if (og + 1u == (tg + 1u) * nx) xb_add(&bar[XB_TOPGEN], 1u);
;     ...
;             xb_add(&bar[XB_XGEN(b.x)], 1u);
.LBB0_233:
	s_or_b64 exec, exec, s[6:7]
	v_mov_b32_e32 v0, 0x2000
	v_mov_b32_e32 v1, 1
	s_waitcnt vmcnt(0)
	buffer_inv sc1
	s_waitcnt vmcnt(0)

; __device__ __forceinline__ unsigned xb_ld(unsigned* p)              { return __hip_atomic_load(p, __ATOMIC_RELAXED, __HIP_MEMORY_SCOPE_AGENT); }
; __device__ __forceinline__ unsigned xb_add(unsigned* p, unsigned v) { return __hip_atomic_fetch_add(p, v, __ATOMIC_RELAXED, __HIP_MEMORY_SCOPE_AGENT); }
; #define XB_SPIN(cond, bar) do { unsigned _sp = 0; while (cond) { __builtin_amdgcn_s_sleep(1); \
;     if ((++_sp & 255u) == 0u) { if (xb_ld(&(bar)[XB_TMO])) break; if (_sp > XB_SPIN_CAP) { atomicAdd(&(bar)[XB_TMO], 1u); break; } } } } while (0)
; __device__ __forceinline__ void xcd_barrier(const XcdBarrier& b) {
;     ...
;         const unsigned old = xb_add(&bar[XB_XSUB(b.x)], 1u);
;         const unsigned gen = old / nloc;
;         if (old + 1u == (gen + 1u) * nloc) {
;             __builtin_amdgcn_fence(__ATOMIC_RELEASE, "agent");
;             asm volatile("s_waitcnt vmcnt(0)" ::: "memory");
;             const unsigned og = xb_add(&bar[XB_TOP], 1u);
;             const unsigned tg = og / nx;
;             if (og + 1u == (tg + 1u) * nx) xb_add(&bar[XB_TOPGEN], 1u);
;             else XB_SPIN(xb_ld(&bar[XB_TOPGEN]) == tg, bar);
;             __builtin_amdgcn_fence(__ATOMIC_ACQUIRE, "agent");
;             xb_add(&bar[XB_XGEN(b.x)], 1u);
;             asm volatile("s_waitcnt vmcnt(0)" ::: "memory");
;         } else {
;             XB_SPIN(xb_ld(&bar[XB_XGEN(b.x)]) == gen, bar);
;             __builtin_amdgcn_fence(__ATOMIC_ACQUIRE, "agent");
;             asm volatile("s_waitcnt vmcnt(0)" ::: "memory");
;         }
.LBB0_279:
	v_readlane_b32 s4, v254, 6
	s_lshl_b32 s4, s4, 8
	v_readlane_b32 s6, v254, 4
	v_readlane_b32 s7, v254, 5
	s_add_u32 s4, s6, s4
	s_addc_u32 s5, s7, 0
	v_mov_b32_e32 v1, 0x1000
	v_mov_b32_e32 v3, 1
	global_atomic_add v3, v1, v3, s[4:5] offset:1024 sc0
	v_cvt_f32_u32_e32 v1, v2
	v_sub_u32_e32 v4, 0, v2
	v_rcp_iflag_f32_e32 v1, v1
	s_nop 0
	v_mul_f32_e32 v1, 0x4f7ffffe, v1
	v_cvt_u32_f32_e32 v1, v1
	v_mul_lo_u32 v4, v4, v1
	v_mul_hi_u32 v4, v1, v4
	v_add_u32_e32 v1, v1, v4
	s_waitcnt vmcnt(0)
	v_mul_hi_u32 v1, v3, v1
	v_mul_lo_u32 v4, v1, v2
	v_sub_u32_e32 v4, v3, v4
	v_add_u32_e32 v5, 1, v1
	v_cmp_ge_u32_e32 vcc, v4, v2
	v_add_u32_e32 v3, 1, v3
	s_nop 0
	v_cndmask_b32_e32 v1, v1, v5, vcc
	v_sub_u32_e32 v5, v4, v2
	v_cndmask_b32_e32 v4, v4, v5, vcc
	v_add_u32_e32 v5, 1, v1
	v_cmp_ge_u32_e32 vcc, v4, v2
	s_nop 1
	v_cndmask_b32_e32 v1, v1, v5, vcc
	v_mul_lo_u32 v4, v2, v1
	v_add_u32_e32 v2, v4, v2
	v_cmp_ne_u32_e32 vcc, v3, v2
	s_and_saveexec_b64 s[6:7], vcc
	s_xor_b64 s[6:7], exec, s[6:7]
	s_cbranch_execz .LBB0_293
	s_waitcnt lgkmcnt(0)
	s_add_u32 s16, s94, 0x83500
	s_addc_u32 s17, s95, 0
	v_mad_u32_u24 v4, v1, v0, v0
	v_mov_b32_e32 v0, 0
	global_load_dword v0, v0, s[16:17] offset:-256 sc1
	s_waitcnt vmcnt(0)
	v_cmp_gt_u32_e32 vcc, v4, v0
	s_and_saveexec_b64 s[8:9], vcc
	s_cbranch_execz .LBB0_292
	s_add_u32 s10, s94, 0x80200
	s_addc_u32 s11, s95, 0
	s_mov_b32 s12, 1
	s_mov_b64 s[20:21], 0
	v_mov_b32_e32 v0, 0
	s_branch .LBB0_283

; __device__ __forceinline__ unsigned xb_ld(unsigned* p)              { return __hip_atomic_load(p, __ATOMIC_RELAXED, __HIP_MEMORY_SCOPE_AGENT); }
; __device__ __forceinline__ unsigned xb_add(unsigned* p, unsigned v) { return __hip_atomic_fetch_add(p, v, __ATOMIC_RELAXED, __HIP_MEMORY_SCOPE_AGENT); }
; #define XB_SPIN(cond, bar) do { unsigned _sp = 0; while (cond) { __builtin_amdgcn_s_sleep(1); \
;     if ((++_sp & 255u) == 0u) { if (xb_ld(&(bar)[XB_TMO])) break; if (_sp > XB_SPIN_CAP) { atomicAdd(&(bar)[XB_TMO], 1u); break; } } } } while (0)
; __device__ __forceinline__ void xcd_barrier(const XcdBarrier& b) {
;     ...
;             else XB_SPIN(xb_ld(&bar[XB_TOPGEN]) == tg, bar);
;             __builtin_amdgcn_fence(__ATOMIC_ACQUIRE, "agent");
;             xb_add(&bar[XB_XGEN(b.x)], 1u);
;             asm volatile("s_waitcnt vmcnt(0)" ::: "memory");
;         } else {
;             XB_SPIN(xb_ld(&bar[XB_XGEN(b.x)]) == gen, bar);
.LBB0_285:
	global_load_dword v2, v0, s[16:17] offset:-256 sc1
	s_add_i32 s12, s12, 1
	s_mov_b64 s[26:27], -1
	s_waitcnt vmcnt(0)
	v_cmp_le_u32_e32 vcc, v4, v2
	s_orn2_b64 s[24:25], vcc, exec
	s_branch .LBB0_282

; __device__ __forceinline__ unsigned xb_ld(unsigned* p)              { return __hip_atomic_load(p, __ATOMIC_RELAXED, __HIP_MEMORY_SCOPE_AGENT); }
; __device__ __forceinline__ unsigned xb_add(unsigned* p, unsigned v) { return __hip_atomic_fetch_add(p, v, __ATOMIC_RELAXED, __HIP_MEMORY_SCOPE_AGENT); }
; #define XB_SPIN(cond, bar) do { unsigned _sp = 0; while (cond) { __builtin_amdgcn_s_sleep(1); \
;     if ((++_sp & 255u) == 0u) { if (xb_ld(&(bar)[XB_TMO])) break; if (_sp > XB_SPIN_CAP) { atomicAdd(&(bar)[XB_TMO], 1u); break; } } } } while (0)
; __device__ __forceinline__ void xcd_barrier(const XcdBarrier& b) {
;     ...
;             asm volatile("s_waitcnt vmcnt(0)" ::: "memory");
;             const unsigned og = xb_add(&bar[XB_TOP], 1u);
;             const unsigned tg = og / nx;
;             if (og + 1u == (tg + 1u) * nx) xb_add(&bar[XB_TOPGEN], 1u);
;             else XB_SPIN(xb_ld(&bar[XB_TOPGEN]) == tg, bar);
;             __builtin_amdgcn_fence(__ATOMIC_ACQUIRE, "agent");
.LBB0_296:
	s_or_b64 exec, exec, s[8:9]
	v_cvt_f32_u32_e32 v3, v0
	s_waitcnt vmcnt(0)
	v_readfirstlane_b32 s6, v2
	s_add_u32 s8, s94, 0x83500
	s_addc_u32 s9, s95, 0
	v_rcp_iflag_f32_e32 v3, v3
	v_add_u32_e32 v1, s6, v1
	v_add_u32_e32 v4, 1, v1
	s_mov_b64 s[10:11], -1
	v_mul_f32_e32 v2, 0x4f7ffffe, v3
	v_cvt_u32_f32_e32 v2, v2
	v_sub_u32_e32 v3, 0, v0
	v_mul_lo_u32 v3, v3, v2
	v_mul_hi_u32 v3, v2, v3
	v_add_u32_e32 v2, v2, v3
	v_mul_hi_u32 v2, v1, v2
	v_mul_lo_u32 v3, v2, v0
	v_sub_u32_e32 v1, v1, v3
	v_add_u32_e32 v5, 1, v2
	v_cmp_ge_u32_e32 vcc, v1, v0
	v_sub_u32_e32 v3, v1, v0
	s_nop 0
	v_cndmask_b32_e32 v2, v2, v5, vcc
	v_cndmask_b32_e32 v1, v1, v3, vcc
	v_add_u32_e32 v3, 1, v2
	v_cmp_ge_u32_e32 vcc, v1, v0
	s_nop 1
	v_cndmask_b32_e32 v2, v2, v3, vcc
	v_mul_lo_u32 v1, v0, v2
	v_add_u32_e32 v0, v1, v0
	v_mov_b32_e32 v5, v0
	v_cmp_ne_u32_e32 vcc, v4, v0
	v_mov_b64_e32 v[0:1], s[8:9]
	s_and_saveexec_b64 s[6:7], vcc
	s_cbranch_execz .LBB0_308
	v_mov_b32_e32 v0, 0
	global_load_dword v1, v0, s[8:9] offset:-256 sc1
	s_mov_b64 s[20:21], 0
	s_waitcnt vmcnt(0)
	v_cmp_gt_u32_e32 vcc, v5, v1
	s_and_saveexec_b64 s[16:17], vcc
	s_cbranch_execz .LBB0_307
	s_add_u32 s10, s94, 0x80200
	s_addc_u32 s11, s95, 0
	s_mov_b32 s12, 1
	s_branch .LBB0_300

; __device__ __forceinline__ unsigned xb_ld(unsigned* p)              { return __hip_atomic_load(p, __ATOMIC_RELAXED, __HIP_MEMORY_SCOPE_AGENT); }
; #define XB_SPIN(cond, bar) do { unsigned _sp = 0; while (cond) { __builtin_amdgcn_s_sleep(1); \
;     if ((++_sp & 255u) == 0u) { if (xb_ld(&(bar)[XB_TMO])) break; if (_sp > XB_SPIN_CAP) { atomicAdd(&(bar)[XB_TMO], 1u); break; } } } } while (0)
; __device__ __forceinline__ void xcd_barrier(const XcdBarrier& b) {
;     ...
;             else XB_SPIN(xb_ld(&bar[XB_TOPGEN]) == tg, bar);
.LBB0_302:
	global_load_dword v1, v0, s[8:9] offset:-256 sc1
	s_add_i32 s12, s12, 1
	s_mov_b64 s[24:25], -1
	s_waitcnt vmcnt(0)
	v_cmp_le_u32_e32 vcc, v5, v1
	s_orn2_b64 s[28:29], vcc, exec
	s_branch .LBB0_299

; __device__ __forceinline__ unsigned xb_ld(unsigned* p)              { return __hip_atomic_load(p, __ATOMIC_RELAXED, __HIP_MEMORY_SCOPE_AGENT); }
; __device__ __forceinline__ unsigned xb_add(unsigned* p, unsigned v) { return __hip_atomic_fetch_add(p, v, __ATOMIC_RELAXED, __HIP_MEMORY_SCOPE_AGENT); }
; #define XB_SPIN(cond, bar) do { unsigned _sp = 0; while (cond) { __builtin_amdgcn_s_sleep(1); \
;     if ((++_sp & 255u) == 0u) { if (xb_ld(&(bar)[XB_TMO])) break; if (_sp > XB_SPIN_CAP) { atomicAdd(&(bar)[XB_TMO], 1u); break; } } } } while (0)
; __device__ __forceinline__ void xcd_barrier(const XcdBarrier& b) {
;     ...
;         const unsigned old = xb_add(&bar[XB_XSUB(b.x)], 1u);
;         const unsigned gen = old / nloc;
;         if (old + 1u == (gen + 1u) * nloc) {
;             __builtin_amdgcn_fence(__ATOMIC_RELEASE, "agent");
;             asm volatile("s_waitcnt vmcnt(0)" ::: "memory");
;             const unsigned og = xb_add(&bar[XB_TOP], 1u);
;             const unsigned tg = og / nx;
;             if (og + 1u == (tg + 1u) * nx) xb_add(&bar[XB_TOPGEN], 1u);
;             else XB_SPIN(xb_ld(&bar[XB_TOPGEN]) == tg, bar);
;             __builtin_amdgcn_fence(__ATOMIC_ACQUIRE, "agent");
;             xb_add(&bar[XB_XGEN(b.x)], 1u);
;             asm volatile("s_waitcnt vmcnt(0)" ::: "memory");
;         } else {
;             XB_SPIN(xb_ld(&bar[XB_XGEN(b.x)]) == gen, bar);
;             __builtin_amdgcn_fence(__ATOMIC_ACQUIRE, "agent");
;             asm volatile("s_waitcnt vmcnt(0)" ::: "memory");
;         }
.LBB0_374:
	v_readlane_b32 s4, v254, 6
	s_lshl_b32 s4, s4, 8
	v_readlane_b32 s6, v254, 4
	v_readlane_b32 s7, v254, 5
	s_add_u32 s4, s6, s4
	s_addc_u32 s5, s7, 0
	v_mov_b32_e32 v1, 0x1000
	v_mov_b32_e32 v3, 1
	global_atomic_add v3, v1, v3, s[4:5] offset:1024 sc0
	v_cvt_f32_u32_e32 v1, v2
	v_sub_u32_e32 v4, 0, v2
	v_rcp_iflag_f32_e32 v1, v1
	s_nop 0
	v_mul_f32_e32 v1, 0x4f7ffffe, v1
	v_cvt_u32_f32_e32 v1, v1
	v_mul_lo_u32 v4, v4, v1
	v_mul_hi_u32 v4, v1, v4
	v_add_u32_e32 v1, v1, v4
	s_waitcnt vmcnt(0)
	v_mul_hi_u32 v1, v3, v1
	v_mul_lo_u32 v4, v1, v2
	v_sub_u32_e32 v4, v3, v4
	v_add_u32_e32 v5, 1, v1
	v_cmp_ge_u32_e32 vcc, v4, v2
	v_add_u32_e32 v3, 1, v3
	s_nop 0
	v_cndmask_b32_e32 v1, v1, v5, vcc
	v_sub_u32_e32 v5, v4, v2
	v_cndmask_b32_e32 v4, v4, v5, vcc
	v_add_u32_e32 v5, 1, v1
	v_cmp_ge_u32_e32 vcc, v4, v2
	s_nop 1
	v_cndmask_b32_e32 v1, v1, v5, vcc
	v_mul_lo_u32 v4, v2, v1
	v_add_u32_e32 v2, v4, v2
	v_cmp_ne_u32_e32 vcc, v3, v2
	s_and_saveexec_b64 s[6:7], vcc
	s_xor_b64 s[6:7], exec, s[6:7]
	s_cbranch_execz .LBB0_388
	s_waitcnt lgkmcnt(0)
	s_add_u32 s20, s94, 0x83500
	s_addc_u32 s21, s95, 0
	v_mad_u32_u24 v4, v1, v0, v0
	v_mov_b32_e32 v0, 0
	global_load_dword v0, v0, s[20:21] offset:-256 sc1
	s_waitcnt vmcnt(0)
	v_cmp_gt_u32_e32 vcc, v4, v0
	s_and_saveexec_b64 s[8:9], vcc
	s_cbranch_execz .LBB0_387
	s_add_u32 s10, s94, 0x80200
	s_addc_u32 s11, s95, 0
	s_mov_b32 s12, 1
	s_mov_b64 s[22:23], 0
	v_mov_b32_e32 v0, 0
	s_branch .LBB0_378

; __device__ __forceinline__ unsigned xb_ld(unsigned* p)              { return __hip_atomic_load(p, __ATOMIC_RELAXED, __HIP_MEMORY_SCOPE_AGENT); }
; __device__ __forceinline__ unsigned xb_add(unsigned* p, unsigned v) { return __hip_atomic_fetch_add(p, v, __ATOMIC_RELAXED, __HIP_MEMORY_SCOPE_AGENT); }
; #define XB_SPIN(cond, bar) do { unsigned _sp = 0; while (cond) { __builtin_amdgcn_s_sleep(1); \
;     if ((++_sp & 255u) == 0u) { if (xb_ld(&(bar)[XB_TMO])) break; if (_sp > XB_SPIN_CAP) { atomicAdd(&(bar)[XB_TMO], 1u); break; } } } } while (0)
; __device__ __forceinline__ void xcd_barrier(const XcdBarrier& b) {
;     ...
;             else XB_SPIN(xb_ld(&bar[XB_TOPGEN]) == tg, bar);
;             __builtin_amdgcn_fence(__ATOMIC_ACQUIRE, "agent");
;             xb_add(&bar[XB_XGEN(b.x)], 1u);
;             asm volatile("s_waitcnt vmcnt(0)" ::: "memory");
;         } else {
;             XB_SPIN(xb_ld(&bar[XB_XGEN(b.x)]) == gen, bar);
.LBB0_380:
	global_load_dword v2, v0, s[20:21] offset:-256 sc1
	s_add_i32 s12, s12, 1
	s_mov_b64 s[28:29], -1
	s_waitcnt vmcnt(0)
	v_cmp_le_u32_e32 vcc, v4, v2
	s_orn2_b64 s[26:27], vcc, exec
	s_branch .LBB0_377

; __device__ __forceinline__ unsigned xb_ld(unsigned* p)              { return __hip_atomic_load(p, __ATOMIC_RELAXED, __HIP_MEMORY_SCOPE_AGENT); }
; __device__ __forceinline__ unsigned xb_add(unsigned* p, unsigned v) { return __hip_atomic_fetch_add(p, v, __ATOMIC_RELAXED, __HIP_MEMORY_SCOPE_AGENT); }
; #define XB_SPIN(cond, bar) do { unsigned _sp = 0; while (cond) { __builtin_amdgcn_s_sleep(1); \
;     if ((++_sp & 255u) == 0u) { if (xb_ld(&(bar)[XB_TMO])) break; if (_sp > XB_SPIN_CAP) { atomicAdd(&(bar)[XB_TMO], 1u); break; } } } } while (0)
; __device__ __forceinline__ void xcd_barrier(const XcdBarrier& b) {
;     ...
;             asm volatile("s_waitcnt vmcnt(0)" ::: "memory");
;             const unsigned og = xb_add(&bar[XB_TOP], 1u);
;             const unsigned tg = og / nx;
;             if (og + 1u == (tg + 1u) * nx) xb_add(&bar[XB_TOPGEN], 1u);
;             else XB_SPIN(xb_ld(&bar[XB_TOPGEN]) == tg, bar);
;             __builtin_amdgcn_fence(__ATOMIC_ACQUIRE, "agent");
.LBB0_391:
	s_or_b64 exec, exec, s[8:9]
	v_cvt_f32_u32_e32 v3, v0
	s_waitcnt vmcnt(0)
	v_readfirstlane_b32 s6, v2
	s_add_u32 s8, s94, 0x83500
	s_addc_u32 s9, s95, 0
	v_rcp_iflag_f32_e32 v3, v3
	v_add_u32_e32 v1, s6, v1
	v_add_u32_e32 v4, 1, v1
	s_mov_b64 s[10:11], -1
	v_mul_f32_e32 v2, 0x4f7ffffe, v3
	v_cvt_u32_f32_e32 v2, v2
	v_sub_u32_e32 v3, 0, v0
	v_mul_lo_u32 v3, v3, v2
	v_mul_hi_u32 v3, v2, v3
	v_add_u32_e32 v2, v2, v3
	v_mul_hi_u32 v2, v1, v2
	v_mul_lo_u32 v3, v2, v0
	v_sub_u32_e32 v1, v1, v3
	v_add_u32_e32 v5, 1, v2
	v_cmp_ge_u32_e32 vcc, v1, v0
	v_sub_u32_e32 v3, v1, v0
	s_nop 0
	v_cndmask_b32_e32 v2, v2, v5, vcc
	v_cndmask_b32_e32 v1, v1, v3, vcc
	v_add_u32_e32 v3, 1, v2
	v_cmp_ge_u32_e32 vcc, v1, v0
	s_nop 1
	v_cndmask_b32_e32 v2, v2, v3, vcc
	v_mul_lo_u32 v1, v0, v2
	v_add_u32_e32 v0, v1, v0
	v_mov_b32_e32 v5, v0
	v_cmp_ne_u32_e32 vcc, v4, v0
	v_mov_b64_e32 v[0:1], s[8:9]
	s_and_saveexec_b64 s[6:7], vcc
	s_cbranch_execz .LBB0_403
	v_mov_b32_e32 v0, 0
	global_load_dword v1, v0, s[8:9] offset:-256 sc1
	s_mov_b64 s[22:23], 0
	s_waitcnt vmcnt(0)
	v_cmp_gt_u32_e32 vcc, v5, v1
	s_and_saveexec_b64 s[20:21], vcc
	s_cbranch_execz .LBB0_402
	s_add_u32 s10, s94, 0x80200
	s_addc_u32 s11, s95, 0
	s_mov_b32 s12, 1
	s_branch .LBB0_395

; __device__ __forceinline__ unsigned xb_ld(unsigned* p)              { return __hip_atomic_load(p, __ATOMIC_RELAXED, __HIP_MEMORY_SCOPE_AGENT); }
; #define XB_SPIN(cond, bar) do { unsigned _sp = 0; while (cond) { __builtin_amdgcn_s_sleep(1); \
;     if ((++_sp & 255u) == 0u) { if (xb_ld(&(bar)[XB_TMO])) break; if (_sp > XB_SPIN_CAP) { atomicAdd(&(bar)[XB_TMO], 1u); break; } } } } while (0)
; __device__ __forceinline__ void xcd_barrier(const XcdBarrier& b) {
;     ...
;             else XB_SPIN(xb_ld(&bar[XB_TOPGEN]) == tg, bar);
.LBB0_397:
	global_load_dword v1, v0, s[8:9] offset:-256 sc1
	s_add_i32 s12, s12, 1
	s_mov_b64 s[26:27], -1
	s_waitcnt vmcnt(0)
	v_cmp_le_u32_e32 vcc, v5, v1
	s_orn2_b64 s[30:31], vcc, exec
	s_branch .LBB0_394

; __device__ __forceinline__ unsigned xb_ld(unsigned* p)              { return __hip_atomic_load(p, __ATOMIC_RELAXED, __HIP_MEMORY_SCOPE_AGENT); }
; __device__ __forceinline__ unsigned xb_add(unsigned* p, unsigned v) { return __hip_atomic_fetch_add(p, v, __ATOMIC_RELAXED, __HIP_MEMORY_SCOPE_AGENT); }
; #define XB_SPIN(cond, bar) do { unsigned _sp = 0; while (cond) { __builtin_amdgcn_s_sleep(1); \
;     if ((++_sp & 255u) == 0u) { if (xb_ld(&(bar)[XB_TMO])) break; if (_sp > XB_SPIN_CAP) { atomicAdd(&(bar)[XB_TMO], 1u); break; } } } } while (0)
; __device__ __forceinline__ void xcd_barrier(const XcdBarrier& b) {
;     ...
;         const unsigned old = xb_add(&bar[XB_XSUB(b.x)], 1u);
;         const unsigned gen = old / nloc;
;         if (old + 1u == (gen + 1u) * nloc) {
;             __builtin_amdgcn_fence(__ATOMIC_RELEASE, "agent");
;             asm volatile("s_waitcnt vmcnt(0)" ::: "memory");
;             const unsigned og = xb_add(&bar[XB_TOP], 1u);
;             const unsigned tg = og / nx;
;             if (og + 1u == (tg + 1u) * nx) xb_add(&bar[XB_TOPGEN], 1u);
;             else XB_SPIN(xb_ld(&bar[XB_TOPGEN]) == tg, bar);
;             __builtin_amdgcn_fence(__ATOMIC_ACQUIRE, "agent");
;             xb_add(&bar[XB_XGEN(b.x)], 1u);
;             asm volatile("s_waitcnt vmcnt(0)" ::: "memory");
;         } else {
;             XB_SPIN(xb_ld(&bar[XB_XGEN(b.x)]) == gen, bar);
;             __builtin_amdgcn_fence(__ATOMIC_ACQUIRE, "agent");
;             asm volatile("s_waitcnt vmcnt(0)" ::: "memory");
;         }
.LBB0_557:
	v_readlane_b32 s4, v254, 6
	s_lshl_b32 s4, s4, 8
	v_readlane_b32 s6, v254, 4
	v_readlane_b32 s7, v254, 5
	s_add_u32 s4, s6, s4
	s_addc_u32 s5, s7, 0
	v_mov_b32_e32 v1, 0x1000
	v_mov_b32_e32 v3, 1
	global_atomic_add v3, v1, v3, s[4:5] offset:1024 sc0
	v_cvt_f32_u32_e32 v1, v2
	v_sub_u32_e32 v4, 0, v2
	v_rcp_iflag_f32_e32 v1, v1
	s_nop 0
	v_mul_f32_e32 v1, 0x4f7ffffe, v1
	v_cvt_u32_f32_e32 v1, v1
	v_mul_lo_u32 v4, v4, v1
	v_mul_hi_u32 v4, v1, v4
	v_add_u32_e32 v1, v1, v4
	s_waitcnt vmcnt(0)
	v_mul_hi_u32 v1, v3, v1
	v_mul_lo_u32 v4, v1, v2
	v_sub_u32_e32 v4, v3, v4
	v_add_u32_e32 v5, 1, v1
	v_cmp_ge_u32_e32 vcc, v4, v2
	v_add_u32_e32 v3, 1, v3
	s_nop 0
	v_cndmask_b32_e32 v1, v1, v5, vcc
	v_sub_u32_e32 v5, v4, v2
	v_cndmask_b32_e32 v4, v4, v5, vcc
	v_add_u32_e32 v5, 1, v1
	v_cmp_ge_u32_e32 vcc, v4, v2
	s_nop 1
	v_cndmask_b32_e32 v1, v1, v5, vcc
	v_mul_lo_u32 v4, v2, v1
	v_add_u32_e32 v2, v4, v2
	v_cmp_ne_u32_e32 vcc, v3, v2
	s_and_saveexec_b64 s[6:7], vcc
	s_xor_b64 s[6:7], exec, s[6:7]
	s_cbranch_execz .LBB0_571
	s_waitcnt lgkmcnt(0)
	s_add_u32 s22, s94, 0x83500
	s_addc_u32 s23, s95, 0
	v_mad_u32_u24 v4, v1, v0, v0
	v_mov_b32_e32 v0, 0
	global_load_dword v0, v0, s[22:23] offset:-256 sc1
	s_waitcnt vmcnt(0)
	v_cmp_gt_u32_e32 vcc, v4, v0
	s_and_saveexec_b64 s[8:9], vcc
	s_cbranch_execz .LBB0_570
	s_add_u32 s10, s94, 0x80200
	s_addc_u32 s11, s95, 0
	s_mov_b32 s12, 1
	s_mov_b64 s[24:25], 0
	v_mov_b32_e32 v0, 0
	s_branch .LBB0_561

; __device__ __forceinline__ unsigned xb_ld(unsigned* p)              { return __hip_atomic_load(p, __ATOMIC_RELAXED, __HIP_MEMORY_SCOPE_AGENT); }
; __device__ __forceinline__ unsigned xb_add(unsigned* p, unsigned v) { return __hip_atomic_fetch_add(p, v, __ATOMIC_RELAXED, __HIP_MEMORY_SCOPE_AGENT); }
; #define XB_SPIN(cond, bar) do { unsigned _sp = 0; while (cond) { __builtin_amdgcn_s_sleep(1); \
;     if ((++_sp & 255u) == 0u) { if (xb_ld(&(bar)[XB_TMO])) break; if (_sp > XB_SPIN_CAP) { atomicAdd(&(bar)[XB_TMO], 1u); break; } } } } while (0)
; __device__ __forceinline__ void xcd_barrier(const XcdBarrier& b) {
;     ...
;             else XB_SPIN(xb_ld(&bar[XB_TOPGEN]) == tg, bar);
;             __builtin_amdgcn_fence(__ATOMIC_ACQUIRE, "agent");
;             xb_add(&bar[XB_XGEN(b.x)], 1u);
;             asm volatile("s_waitcnt vmcnt(0)" ::: "memory");
;         } else {
;             XB_SPIN(xb_ld(&bar[XB_XGEN(b.x)]) == gen, bar);
.LBB0_563:
	global_load_dword v2, v0, s[22:23] offset:-256 sc1
	s_add_i32 s12, s12, 1
	s_mov_b64 s[30:31], -1
	s_waitcnt vmcnt(0)
	v_cmp_le_u32_e32 vcc, v4, v2
	s_orn2_b64 s[28:29], vcc, exec
	s_branch .LBB0_560

; __device__ __forceinline__ unsigned xb_ld(unsigned* p)              { return __hip_atomic_load(p, __ATOMIC_RELAXED, __HIP_MEMORY_SCOPE_AGENT); }
; __device__ __forceinline__ unsigned xb_add(unsigned* p, unsigned v) { return __hip_atomic_fetch_add(p, v, __ATOMIC_RELAXED, __HIP_MEMORY_SCOPE_AGENT); }
; #define XB_SPIN(cond, bar) do { unsigned _sp = 0; while (cond) { __builtin_amdgcn_s_sleep(1); \
;     if ((++_sp & 255u) == 0u) { if (xb_ld(&(bar)[XB_TMO])) break; if (_sp > XB_SPIN_CAP) { atomicAdd(&(bar)[XB_TMO], 1u); break; } } } } while (0)
; __device__ __forceinline__ void xcd_barrier(const XcdBarrier& b) {
;     ...
;             asm volatile("s_waitcnt vmcnt(0)" ::: "memory");
;             const unsigned og = xb_add(&bar[XB_TOP], 1u);
;             const unsigned tg = og / nx;
;             if (og + 1u == (tg + 1u) * nx) xb_add(&bar[XB_TOPGEN], 1u);
;             else XB_SPIN(xb_ld(&bar[XB_TOPGEN]) == tg, bar);
;             __builtin_amdgcn_fence(__ATOMIC_ACQUIRE, "agent");
.LBB0_574:
	s_or_b64 exec, exec, s[8:9]
	v_cvt_f32_u32_e32 v3, v0
	s_waitcnt vmcnt(0)
	v_readfirstlane_b32 s6, v2
	s_add_u32 s8, s94, 0x83500
	s_addc_u32 s9, s95, 0
	v_rcp_iflag_f32_e32 v3, v3
	v_add_u32_e32 v1, s6, v1
	v_add_u32_e32 v4, 1, v1
	s_mov_b64 s[10:11], -1
	v_mul_f32_e32 v2, 0x4f7ffffe, v3
	v_cvt_u32_f32_e32 v2, v2
	v_sub_u32_e32 v3, 0, v0
	v_mul_lo_u32 v3, v3, v2
	v_mul_hi_u32 v3, v2, v3
	v_add_u32_e32 v2, v2, v3
	v_mul_hi_u32 v2, v1, v2
	v_mul_lo_u32 v3, v2, v0
	v_sub_u32_e32 v1, v1, v3
	v_add_u32_e32 v5, 1, v2
	v_cmp_ge_u32_e32 vcc, v1, v0
	v_sub_u32_e32 v3, v1, v0
	s_nop 0
	v_cndmask_b32_e32 v2, v2, v5, vcc
	v_cndmask_b32_e32 v1, v1, v3, vcc
	v_add_u32_e32 v3, 1, v2
	v_cmp_ge_u32_e32 vcc, v1, v0
	s_nop 1
	v_cndmask_b32_e32 v2, v2, v3, vcc
	v_mul_lo_u32 v1, v0, v2
	v_add_u32_e32 v0, v1, v0
	v_mov_b32_e32 v5, v0
	v_cmp_ne_u32_e32 vcc, v4, v0
	v_mov_b64_e32 v[0:1], s[8:9]
	s_and_saveexec_b64 s[6:7], vcc
	s_cbranch_execz .LBB0_586
	v_mov_b32_e32 v0, 0
	global_load_dword v1, v0, s[8:9] offset:-256 sc1
	s_mov_b64 s[24:25], 0
	s_waitcnt vmcnt(0)
	v_cmp_gt_u32_e32 vcc, v5, v1
	s_and_saveexec_b64 s[22:23], vcc
	s_cbranch_execz .LBB0_585
	s_add_u32 s10, s94, 0x80200
	s_addc_u32 s11, s95, 0
	s_mov_b32 s12, 1
	s_branch .LBB0_578

; __device__ __forceinline__ unsigned xb_ld(unsigned* p)              { return __hip_atomic_load(p, __ATOMIC_RELAXED, __HIP_MEMORY_SCOPE_AGENT); }
; #define XB_SPIN(cond, bar) do { unsigned _sp = 0; while (cond) { __builtin_amdgcn_s_sleep(1); \
;     if ((++_sp & 255u) == 0u) { if (xb_ld(&(bar)[XB_TMO])) break; if (_sp > XB_SPIN_CAP) { atomicAdd(&(bar)[XB_TMO], 1u); break; } } } } while (0)
; __device__ __forceinline__ void xcd_barrier(const XcdBarrier& b) {
;     ...
;             else XB_SPIN(xb_ld(&bar[XB_TOPGEN]) == tg, bar);
.LBB0_580:
	global_load_dword v1, v0, s[8:9] offset:-256 sc1
	s_add_i32 s12, s12, 1
	s_mov_b64 s[28:29], -1
	s_waitcnt vmcnt(0)
	v_cmp_le_u32_e32 vcc, v5, v1
	s_orn2_b64 s[34:35], vcc, exec
	s_branch .LBB0_577

; __device__ __forceinline__ unsigned xb_ld(unsigned* p)              { return __hip_atomic_load(p, __ATOMIC_RELAXED, __HIP_MEMORY_SCOPE_AGENT); }
; __device__ __forceinline__ unsigned xb_add(unsigned* p, unsigned v) { return __hip_atomic_fetch_add(p, v, __ATOMIC_RELAXED, __HIP_MEMORY_SCOPE_AGENT); }
; #define XB_SPIN(cond, bar) do { unsigned _sp = 0; while (cond) { __builtin_amdgcn_s_sleep(1); \
;     if ((++_sp & 255u) == 0u) { if (xb_ld(&(bar)[XB_TMO])) break; if (_sp > XB_SPIN_CAP) { atomicAdd(&(bar)[XB_TMO], 1u); break; } } } } while (0)
; __device__ __forceinline__ void xcd_barrier(const XcdBarrier& b) {
;     ...
;         const unsigned old = xb_add(&bar[XB_XSUB(b.x)], 1u);
;         const unsigned gen = old / nloc;
;         if (old + 1u == (gen + 1u) * nloc) {
;             __builtin_amdgcn_fence(__ATOMIC_RELEASE, "agent");
;             asm volatile("s_waitcnt vmcnt(0)" ::: "memory");
;             const unsigned og = xb_add(&bar[XB_TOP], 1u);
;             const unsigned tg = og / nx;
;             if (og + 1u == (tg + 1u) * nx) xb_add(&bar[XB_TOPGEN], 1u);
;             else XB_SPIN(xb_ld(&bar[XB_TOPGEN]) == tg, bar);
;             __builtin_amdgcn_fence(__ATOMIC_ACQUIRE, "agent");
;             xb_add(&bar[XB_XGEN(b.x)], 1u);
;             asm volatile("s_waitcnt vmcnt(0)" ::: "memory");
;         } else {
;             XB_SPIN(xb_ld(&bar[XB_XGEN(b.x)]) == gen, bar);
;             __builtin_amdgcn_fence(__ATOMIC_ACQUIRE, "agent");
;             asm volatile("s_waitcnt vmcnt(0)" ::: "memory");
;         }
.LBB0_1313:
	v_readlane_b32 s4, v254, 6
	s_lshl_b32 s4, s4, 8
	v_readlane_b32 s6, v254, 4
	v_readlane_b32 s7, v254, 5
	s_add_u32 s4, s6, s4
	s_addc_u32 s5, s7, 0
	v_mov_b32_e32 v1, 0x1000
	v_mov_b32_e32 v3, 1
	global_atomic_add v3, v1, v3, s[4:5] offset:1024 sc0
	v_cvt_f32_u32_e32 v1, v2
	v_sub_u32_e32 v4, 0, v2
	v_rcp_iflag_f32_e32 v1, v1
	s_nop 0
	v_mul_f32_e32 v1, 0x4f7ffffe, v1
	v_cvt_u32_f32_e32 v1, v1
	v_mul_lo_u32 v4, v4, v1
	v_mul_hi_u32 v4, v1, v4
	v_add_u32_e32 v1, v1, v4
	s_waitcnt vmcnt(0)
	v_mul_hi_u32 v1, v3, v1
	v_mul_lo_u32 v4, v1, v2
	v_sub_u32_e32 v4, v3, v4
	v_add_u32_e32 v5, 1, v1
	v_cmp_ge_u32_e32 vcc, v4, v2
	v_add_u32_e32 v3, 1, v3
	s_nop 0
	v_cndmask_b32_e32 v1, v1, v5, vcc
	v_sub_u32_e32 v5, v4, v2
	v_cndmask_b32_e32 v4, v4, v5, vcc
	v_add_u32_e32 v5, 1, v1
	v_cmp_ge_u32_e32 vcc, v4, v2
	s_nop 1
	v_cndmask_b32_e32 v1, v1, v5, vcc
	v_mul_lo_u32 v4, v2, v1
	v_add_u32_e32 v2, v4, v2
	v_cmp_ne_u32_e32 vcc, v3, v2
	s_and_saveexec_b64 s[6:7], vcc
	s_xor_b64 s[6:7], exec, s[6:7]
	s_cbranch_execz .LBB0_1327
	s_waitcnt lgkmcnt(0)
	s_add_u32 s18, s94, 0x83500
	s_addc_u32 s19, s95, 0
	v_mad_u32_u24 v4, v1, v0, v0
	v_mov_b32_e32 v0, 0
	global_load_dword v0, v0, s[18:19] offset:-256 sc1
	s_waitcnt vmcnt(0)
	v_cmp_gt_u32_e32 vcc, v4, v0
	s_and_saveexec_b64 s[8:9], vcc
	s_cbranch_execz .LBB0_1326
	s_add_u32 s10, s94, 0x80200
	s_addc_u32 s11, s95, 0
	s_mov_b32 s12, 1
	s_mov_b64 s[22:23], 0
	v_mov_b32_e32 v0, 0
	s_branch .LBB0_1317

; __device__ __forceinline__ unsigned xb_ld(unsigned* p)              { return __hip_atomic_load(p, __ATOMIC_RELAXED, __HIP_MEMORY_SCOPE_AGENT); }
; __device__ __forceinline__ unsigned xb_add(unsigned* p, unsigned v) { return __hip_atomic_fetch_add(p, v, __ATOMIC_RELAXED, __HIP_MEMORY_SCOPE_AGENT); }
; #define XB_SPIN(cond, bar) do { unsigned _sp = 0; while (cond) { __builtin_amdgcn_s_sleep(1); \
;     if ((++_sp & 255u) == 0u) { if (xb_ld(&(bar)[XB_TMO])) break; if (_sp > XB_SPIN_CAP) { atomicAdd(&(bar)[XB_TMO], 1u); break; } } } } while (0)
; __device__ __forceinline__ void xcd_barrier(const XcdBarrier& b) {
;     ...
;             else XB_SPIN(xb_ld(&bar[XB_TOPGEN]) == tg, bar);
;             __builtin_amdgcn_fence(__ATOMIC_ACQUIRE, "agent");
;             xb_add(&bar[XB_XGEN(b.x)], 1u);
;             asm volatile("s_waitcnt vmcnt(0)" ::: "memory");
;         } else {
;             XB_SPIN(xb_ld(&bar[XB_XGEN(b.x)]) == gen, bar);
.LBB0_1319:
	global_load_dword v2, v0, s[18:19] offset:-256 sc1
	s_add_i32 s12, s12, 1
	s_mov_b64 s[28:29], -1
	s_waitcnt vmcnt(0)
	v_cmp_le_u32_e32 vcc, v4, v2
	s_orn2_b64 s[26:27], vcc, exec
	s_branch .LBB0_1316

; __device__ __forceinline__ unsigned xb_ld(unsigned* p)              { return __hip_atomic_load(p, __ATOMIC_RELAXED, __HIP_MEMORY_SCOPE_AGENT); }
; __device__ __forceinline__ unsigned xb_add(unsigned* p, unsigned v) { return __hip_atomic_fetch_add(p, v, __ATOMIC_RELAXED, __HIP_MEMORY_SCOPE_AGENT); }
; #define XB_SPIN(cond, bar) do { unsigned _sp = 0; while (cond) { __builtin_amdgcn_s_sleep(1); \
;     if ((++_sp & 255u) == 0u) { if (xb_ld(&(bar)[XB_TMO])) break; if (_sp > XB_SPIN_CAP) { atomicAdd(&(bar)[XB_TMO], 1u); break; } } } } while (0)
; __device__ __forceinline__ void xcd_barrier(const XcdBarrier& b) {
;     ...
;             asm volatile("s_waitcnt vmcnt(0)" ::: "memory");
;             const unsigned og = xb_add(&bar[XB_TOP], 1u);
;             const unsigned tg = og / nx;
;             if (og + 1u == (tg + 1u) * nx) xb_add(&bar[XB_TOPGEN], 1u);
;             else XB_SPIN(xb_ld(&bar[XB_TOPGEN]) == tg, bar);
;             __builtin_amdgcn_fence(__ATOMIC_ACQUIRE, "agent");
.LBB0_1330:
	s_or_b64 exec, exec, s[8:9]
	v_cvt_f32_u32_e32 v3, v0
	s_waitcnt vmcnt(0)
	v_readfirstlane_b32 s6, v2
	s_add_u32 s8, s94, 0x83500
	s_addc_u32 s9, s95, 0
	v_rcp_iflag_f32_e32 v3, v3
	v_add_u32_e32 v1, s6, v1
	v_add_u32_e32 v4, 1, v1
	s_mov_b64 s[10:11], -1
	v_mul_f32_e32 v2, 0x4f7ffffe, v3
	v_cvt_u32_f32_e32 v2, v2
	v_sub_u32_e32 v3, 0, v0
	v_mul_lo_u32 v3, v3, v2
	v_mul_hi_u32 v3, v2, v3
	v_add_u32_e32 v2, v2, v3
	v_mul_hi_u32 v2, v1, v2
	v_mul_lo_u32 v3, v2, v0
	v_sub_u32_e32 v1, v1, v3
	v_add_u32_e32 v5, 1, v2
	v_cmp_ge_u32_e32 vcc, v1, v0
	v_sub_u32_e32 v3, v1, v0
	s_nop 0
	v_cndmask_b32_e32 v2, v2, v5, vcc
	v_cndmask_b32_e32 v1, v1, v3, vcc
	v_add_u32_e32 v3, 1, v2
	v_cmp_ge_u32_e32 vcc, v1, v0
	s_nop 1
	v_cndmask_b32_e32 v2, v2, v3, vcc
	v_mul_lo_u32 v1, v0, v2
	v_add_u32_e32 v0, v1, v0
	v_mov_b32_e32 v5, v0
	v_cmp_ne_u32_e32 vcc, v4, v0
	v_mov_b64_e32 v[0:1], s[8:9]
	s_and_saveexec_b64 s[6:7], vcc
	s_cbranch_execz .LBB0_1342
	v_mov_b32_e32 v0, 0
	global_load_dword v1, v0, s[8:9] offset:-256 sc1
	s_mov_b64 s[22:23], 0
	s_waitcnt vmcnt(0)
	v_cmp_gt_u32_e32 vcc, v5, v1
	s_and_saveexec_b64 s[18:19], vcc
	s_cbranch_execz .LBB0_1341
	s_add_u32 s10, s94, 0x80200
	s_addc_u32 s11, s95, 0
	s_mov_b32 s12, 1
	s_branch .LBB0_1334

; __device__ __forceinline__ unsigned xb_ld(unsigned* p)              { return __hip_atomic_load(p, __ATOMIC_RELAXED, __HIP_MEMORY_SCOPE_AGENT); }
; __device__ __forceinline__ unsigned xb_add(unsigned* p, unsigned v) { return __hip_atomic_fetch_add(p, v, __ATOMIC_RELAXED, __HIP_MEMORY_SCOPE_AGENT); }
; #define XB_SPIN(cond, bar) do { unsigned _sp = 0; while (cond) { __builtin_amdgcn_s_sleep(1); \
;     if ((++_sp & 255u) == 0u) { if (xb_ld(&(bar)[XB_TMO])) break; if (_sp > XB_SPIN_CAP) { atomicAdd(&(bar)[XB_TMO], 1u); break; } } } } while (0)
; __device__ __forceinline__ void xcd_barrier(const XcdBarrier& b) {
;     ...
;         const unsigned old = xb_add(&bar[XB_XSUB(b.x)], 1u);
;         const unsigned gen = old / nloc;
;         if (old + 1u == (gen + 1u) * nloc) {
;             __builtin_amdgcn_fence(__ATOMIC_RELEASE, "agent");
;             asm volatile("s_waitcnt vmcnt(0)" ::: "memory");
;             const unsigned og = xb_add(&bar[XB_TOP], 1u);
;             const unsigned tg = og / nx;
;             if (og + 1u == (tg + 1u) * nx) xb_add(&bar[XB_TOPGEN], 1u);
;             else XB_SPIN(xb_ld(&bar[XB_TOPGEN]) == tg, bar);
;             __builtin_amdgcn_fence(__ATOMIC_ACQUIRE, "agent");
;             xb_add(&bar[XB_XGEN(b.x)], 1u);
;             asm volatile("s_waitcnt vmcnt(0)" ::: "memory");
;         } else {
;             XB_SPIN(xb_ld(&bar[XB_XGEN(b.x)]) == gen, bar);
;             __builtin_amdgcn_fence(__ATOMIC_ACQUIRE, "agent");
;             asm volatile("s_waitcnt vmcnt(0)" ::: "memory");
;         }
.LBB0_1461:
	v_readlane_b32 s2, v254, 6
	s_lshl_b32 s2, s2, 8
	v_readlane_b32 s4, v254, 4
	v_readlane_b32 s5, v254, 5
	s_add_u32 s2, s4, s2
	s_addc_u32 s3, s5, 0
	v_mov_b32_e32 v1, 0x1000
	v_mov_b32_e32 v3, 1
	global_atomic_add v3, v1, v3, s[2:3] offset:1024 sc0
	v_cvt_f32_u32_e32 v1, v2
	v_sub_u32_e32 v4, 0, v2
	v_rcp_iflag_f32_e32 v1, v1
	s_nop 0
	v_mul_f32_e32 v1, 0x4f7ffffe, v1
	v_cvt_u32_f32_e32 v1, v1
	v_mul_lo_u32 v4, v4, v1
	v_mul_hi_u32 v4, v1, v4
	v_add_u32_e32 v1, v1, v4
	s_waitcnt vmcnt(0)
	v_mul_hi_u32 v1, v3, v1
	v_mul_lo_u32 v4, v1, v2
	v_sub_u32_e32 v4, v3, v4
	v_add_u32_e32 v5, 1, v1
	v_cmp_ge_u32_e32 vcc, v4, v2
	v_add_u32_e32 v3, 1, v3
	s_nop 0
	v_cndmask_b32_e32 v1, v1, v5, vcc
	v_sub_u32_e32 v5, v4, v2
	v_cndmask_b32_e32 v4, v4, v5, vcc
	v_add_u32_e32 v5, 1, v1
	v_cmp_ge_u32_e32 vcc, v4, v2
	s_nop 1
	v_cndmask_b32_e32 v1, v1, v5, vcc
	v_mul_lo_u32 v4, v2, v1
	v_add_u32_e32 v2, v4, v2
	v_cmp_ne_u32_e32 vcc, v3, v2
	s_and_saveexec_b64 s[4:5], vcc
	s_xor_b64 s[4:5], exec, s[4:5]
	s_cbranch_execz .LBB0_1475
	s_waitcnt lgkmcnt(0)
	s_add_u32 s10, s94, 0x83500
	s_addc_u32 s11, s95, 0
	v_mad_u32_u24 v4, v1, v0, v0
	v_mov_b32_e32 v0, 0
	global_load_dword v0, v0, s[10:11] offset:-256 sc1
	s_waitcnt vmcnt(0)
	v_cmp_gt_u32_e32 vcc, v4, v0
	s_and_saveexec_b64 s[6:7], vcc
	s_cbranch_execz .LBB0_1474
	s_add_u32 s8, s94, 0x80200
	s_addc_u32 s9, s95, 0
	s_mov_b32 s12, 1
	s_mov_b64 s[14:15], 0
	v_mov_b32_e32 v0, 0
	s_branch .LBB0_1465

; __device__ __forceinline__ unsigned xb_ld(unsigned* p)              { return __hip_atomic_load(p, __ATOMIC_RELAXED, __HIP_MEMORY_SCOPE_AGENT); }
; __device__ __forceinline__ unsigned xb_add(unsigned* p, unsigned v) { return __hip_atomic_fetch_add(p, v, __ATOMIC_RELAXED, __HIP_MEMORY_SCOPE_AGENT); }
; #define XB_SPIN(cond, bar) do { unsigned _sp = 0; while (cond) { __builtin_amdgcn_s_sleep(1); \
;     if ((++_sp & 255u) == 0u) { if (xb_ld(&(bar)[XB_TMO])) break; if (_sp > XB_SPIN_CAP) { atomicAdd(&(bar)[XB_TMO], 1u); break; } } } } while (0)
; __device__ __forceinline__ void xcd_barrier(const XcdBarrier& b) {
;     ...
;             else XB_SPIN(xb_ld(&bar[XB_TOPGEN]) == tg, bar);
;             __builtin_amdgcn_fence(__ATOMIC_ACQUIRE, "agent");
;             xb_add(&bar[XB_XGEN(b.x)], 1u);
;             asm volatile("s_waitcnt vmcnt(0)" ::: "memory");
;         } else {
;             XB_SPIN(xb_ld(&bar[XB_XGEN(b.x)]) == gen, bar);
.LBB0_1467:
	global_load_dword v2, v0, s[10:11] offset:-256 sc1
	s_add_i32 s12, s12, 1
	s_mov_b64 s[20:21], -1
	s_waitcnt vmcnt(0)
	v_cmp_le_u32_e32 vcc, v4, v2
	s_orn2_b64 s[18:19], vcc, exec
	s_branch .LBB0_1464

; __device__ __forceinline__ unsigned xb_ld(unsigned* p)              { return __hip_atomic_load(p, __ATOMIC_RELAXED, __HIP_MEMORY_SCOPE_AGENT); }
; __device__ __forceinline__ unsigned xb_add(unsigned* p, unsigned v) { return __hip_atomic_fetch_add(p, v, __ATOMIC_RELAXED, __HIP_MEMORY_SCOPE_AGENT); }
; #define XB_SPIN(cond, bar) do { unsigned _sp = 0; while (cond) { __builtin_amdgcn_s_sleep(1); \
;     if ((++_sp & 255u) == 0u) { if (xb_ld(&(bar)[XB_TMO])) break; if (_sp > XB_SPIN_CAP) { atomicAdd(&(bar)[XB_TMO], 1u); break; } } } } while (0)
; __device__ __forceinline__ void xcd_barrier(const XcdBarrier& b) {
;     ...
;             asm volatile("s_waitcnt vmcnt(0)" ::: "memory");
;             const unsigned og = xb_add(&bar[XB_TOP], 1u);
;             const unsigned tg = og / nx;
;             if (og + 1u == (tg + 1u) * nx) xb_add(&bar[XB_TOPGEN], 1u);
;             else XB_SPIN(xb_ld(&bar[XB_TOPGEN]) == tg, bar);
;             __builtin_amdgcn_fence(__ATOMIC_ACQUIRE, "agent");
.LBB0_1478:
	s_or_b64 exec, exec, s[6:7]
	v_cvt_f32_u32_e32 v3, v0
	s_waitcnt vmcnt(0)
	v_readfirstlane_b32 s4, v2
	s_add_u32 s6, s94, 0x83500
	s_addc_u32 s7, s95, 0
	v_rcp_iflag_f32_e32 v3, v3
	v_add_u32_e32 v1, s4, v1
	v_add_u32_e32 v4, 1, v1
	s_mov_b64 s[8:9], -1
	v_mul_f32_e32 v2, 0x4f7ffffe, v3
	v_cvt_u32_f32_e32 v2, v2
	v_sub_u32_e32 v3, 0, v0
	v_mul_lo_u32 v3, v3, v2
	v_mul_hi_u32 v3, v2, v3
	v_add_u32_e32 v2, v2, v3
	v_mul_hi_u32 v2, v1, v2
	v_mul_lo_u32 v3, v2, v0
	v_sub_u32_e32 v1, v1, v3
	v_add_u32_e32 v5, 1, v2
	v_cmp_ge_u32_e32 vcc, v1, v0
	v_sub_u32_e32 v3, v1, v0
	s_nop 0
	v_cndmask_b32_e32 v2, v2, v5, vcc
	v_cndmask_b32_e32 v1, v1, v3, vcc
	v_add_u32_e32 v3, 1, v2
	v_cmp_ge_u32_e32 vcc, v1, v0
	s_nop 1
	v_cndmask_b32_e32 v2, v2, v3, vcc
	v_mul_lo_u32 v1, v0, v2
	v_add_u32_e32 v0, v1, v0
	v_mov_b32_e32 v5, v0
	v_cmp_ne_u32_e32 vcc, v4, v0
	v_mov_b64_e32 v[0:1], s[6:7]
	s_and_saveexec_b64 s[4:5], vcc
	s_cbranch_execz .LBB0_1490
	v_mov_b32_e32 v0, 0
	global_load_dword v1, v0, s[6:7] offset:-256 sc1
	s_mov_b64 s[14:15], 0
	s_waitcnt vmcnt(0)
	v_cmp_gt_u32_e32 vcc, v5, v1
	s_and_saveexec_b64 s[10:11], vcc
	s_cbranch_execz .LBB0_1489
	s_add_u32 s8, s94, 0x80200
	s_addc_u32 s9, s95, 0
	s_mov_b32 s12, 1
	s_branch .LBB0_1482

; __device__ __forceinline__ unsigned xb_ld(unsigned* p)              { return __hip_atomic_load(p, __ATOMIC_RELAXED, __HIP_MEMORY_SCOPE_AGENT); }
; #define XB_SPIN(cond, bar) do { unsigned _sp = 0; while (cond) { __builtin_amdgcn_s_sleep(1); \
;     if ((++_sp & 255u) == 0u) { if (xb_ld(&(bar)[XB_TMO])) break; if (_sp > XB_SPIN_CAP) { atomicAdd(&(bar)[XB_TMO], 1u); break; } } } } while (0)
; __device__ __forceinline__ void xcd_barrier(const XcdBarrier& b) {
;     ...
;             else XB_SPIN(xb_ld(&bar[XB_TOPGEN]) == tg, bar);
.LBB0_1484:
	global_load_dword v1, v0, s[6:7] offset:-256 sc1
	s_add_i32 s12, s12, 1
	s_mov_b64 s[18:19], -1
	s_waitcnt vmcnt(0)
	v_cmp_le_u32_e32 vcc, v5, v1
	s_orn2_b64 s[22:23], vcc, exec
	s_branch .LBB0_1481

; __device__ __forceinline__ unsigned xb_add(unsigned* p, unsigned v) { return __hip_atomic_fetch_add(p, v, __ATOMIC_RELAXED, __HIP_MEMORY_SCOPE_AGENT); }
; __device__ __forceinline__ void xcd_barrier(const XcdBarrier& b) {
;     ...
;             if (og + 1u == (tg + 1u) * nx) xb_add(&bar[XB_TOPGEN], 1u);
;     ...
;             xb_add(&bar[XB_XGEN(b.x)], 1u);
.LBB0_1492:
	s_or_b64 exec, exec, s[4:5]
	v_mov_b32_e32 v0, 0x2000
	v_mov_b32_e32 v1, 1
	s_waitcnt vmcnt(0)
	buffer_inv sc1
	s_waitcnt vmcnt(0)
